# waitcnt placement: the lgkmcnt(7) waits between the K-fragment reads of the SEL/WIN/unitB block heads removed (the steps' counted waits cover them)
# speedup vs baseline: 1.0036x; 1.0008x over previous
; __device__ __forceinline__ int swz(int R) { return (R & 2) | ((R & 8) >> 1); }
; __device__ __forceinline__ void load_kfrags(bf16x8 (&kf)[4][2], const unsigned char* Ks, int r, int fq) {
; #pragma unroll
;     for (int f = 0; f < 4; ++f)
; #pragma unroll
;         for (int dc = 0; dc < 2; ++dc) { const int R = prow(f, r); kf[f][dc] = *(const bf16x8*)(Ks + R * 128 + (((4 * dc + fq) ^ swz(R)) << 4)); }
; }
; __device__ __forceinline__ void qk(f32x4 (&s)[4], const bf16x8 (&kf)[4][2], const bf16x8 (&q)[2], float cinit) {
; #pragma unroll
;     for (int f = 0; f < 4; ++f) {
;         s[f] = (f32x4){cinit, cinit, cinit, cinit};
; #pragma unroll
;         for (int dc = 0; dc < 2; ++dc) s[f] = __builtin_amdgcn_mfma_f32_16x16x32_bf16(kf[f][dc], q[dc], s[f], 0, 0, 0);
;     }
; }
; template <bool SEL> ...
;     ...
;                 const unsigned char* Ks = lds + OFF_RING + slot * SLOTB; const unsigned char* Vs = Ks + 8192;
;                 bf16x8 kf[4][2]; load_kfrags(kf, Ks, r, fq);
;                 const bool edge = (j >= T - 2) || (wl == 512 && j == T - 8);
;                 if (edge) {
.LBB0_2146:
	v_add_u32_e32 v143, 0, v0
	v_add_u32_e32 v142, 0, v138
	ds_read_b128 v[78:81], v143
	ds_read_b128 v[70:73], v143 offset:512
	ds_read_b128 v[74:77], v142
	ds_read_b128 v[66:69], v142 offset:512
	ds_read_b128 v[62:65], v143 offset:4096
	ds_read_b128 v[50:53], v143 offset:4608
	ds_read_b128 v[58:61], v142 offset:4096
	ds_read_b128 v[54:57], v142 offset:4608
	s_cmp_lt_i32 s35, s4
	s_mov_b64 s[8:9], -1
	s_cbranch_scc1 .LBB0_2214
	s_branch .Lub_edge
	s_waitcnt lgkmcnt(7)
	v_mfma_f32_16x16x32_bf16 v[82:85], v[78:81], v[2:5], 0
	v_cmp_gt_u32_e32 vcc, s33, v140
	v_mov_b32_e32 v144, 0xf149f2ca
	v_add_u32_e32 v99, 0, v141
	s_waitcnt lgkmcnt(5)
	v_mfma_f32_16x16x32_bf16 v[94:97], v[74:77], v[6:9], v[82:85]
	v_mov_b32_e32 v145, 0xf149f2ca
	v_mfma_f32_16x16x32_bf16 v[82:85], v[70:73], v[2:5], 0
	s_waitcnt lgkmcnt(4)
	v_mfma_f32_16x16x32_bf16 v[90:93], v[66:69], v[6:9], v[82:85]
	s_waitcnt lgkmcnt(3)
	v_mfma_f32_16x16x32_bf16 v[82:85], v[62:65], v[2:5], 0
	s_waitcnt lgkmcnt(1)
	v_mfma_f32_16x16x32_bf16 v[86:89], v[58:61], v[6:9], v[82:85]
	v_mfma_f32_16x16x32_bf16 v[82:85], v[50:53], v[2:5], 0
	s_waitcnt lgkmcnt(0)
	v_mfma_f32_16x16x32_bf16 v[82:85], v[54:57], v[6:9], v[82:85]
	s_and_saveexec_b64 s[8:9], vcc
	s_cbranch_execz .LBB0_2149
	ds_read_b32 v98, v99
	s_waitcnt lgkmcnt(0)
	v_add_f32_e32 v145, v94, v98

; __device__ __forceinline__ int swz(int R) { return (R & 2) | ((R & 8) >> 1); }
; __device__ __forceinline__ void load_kfrags(bf16x8 (&kf)[4][2], const unsigned char* Ks, int r, int fq) {
; #pragma unroll
;     for (int f = 0; f < 4; ++f)
; #pragma unroll
;         for (int dc = 0; dc < 2; ++dc) { const int R = prow(f, r); kf[f][dc] = *(const bf16x8*)(Ks + R * 128 + (((4 * dc + fq) ^ swz(R)) << 4)); }
; }
; __device__ __forceinline__ void qk(f32x4 (&s)[4], const bf16x8 (&kf)[4][2], const bf16x8 (&q)[2], float cinit) {
; #pragma unroll
;     for (int f = 0; f < 4; ++f) {
;         s[f] = (f32x4){cinit, cinit, cinit, cinit};
; #pragma unroll
;         for (int dc = 0; dc < 2; ++dc) s[f] = __builtin_amdgcn_mfma_f32_16x16x32_bf16(kf[f][dc], q[dc], s[f], 0, 0, 0);
; template <bool SEL> ...
;     ...
;             if (SEL) {
; #pragma unroll
;                 for (int cg_ = 0; cg_ < 2; ++cg_) {
;                     const unsigned long long wsel = j < 64 ? sw[cg_][0] : sw[cg_][1];
;                     selq[cg_] = ((wsel >> (j & 63)) & 1ull) != 0ull; any[cg_] = __any(selq[cg_]) != 0;
;                 }
;             }
;             if (any[0] || any[1]) {
;                 const unsigned char* Ks = lds + OFF_RING + slot * SLOTB; const unsigned char* Vs = Ks + 8192;
;                 bf16x8 kf[4][2]; load_kfrags(kf, Ks, r, fq);
;                 const bool edge = (j >= T - 2) || (wl == 512 && j == T - 8);
;                 if (edge) {
.Lselm_t:
	v_cmp_ne_u32_e64 s[10:11], 0, v60
	v_cmp_ne_u32_e64 s[8:9], 0, v61
	s_or_b64 s[6:7], s[10:11], s[8:9]
	s_cbranch_scc0 .LBB0_2481
	s_and_b32 s6, s49, 0xc000
	v_add_u32_e32 v60, s6, v140
	v_add_u32_e32 v143, v60, v136
	v_add_u32_e32 v142, v60, v137
	ds_read_b128 v[88:91], v143
	ds_read_b128 v[80:83], v143 offset:512
	ds_read_b128 v[84:87], v142
	ds_read_b128 v[76:79], v142 offset:512
	ds_read_b128 v[72:75], v143 offset:4096
	ds_read_b128 v[60:63], v143 offset:4608
	ds_read_b128 v[68:71], v142 offset:4096
	ds_read_b128 v[64:67], v142 offset:4608
	s_cmp_lt_i32 s48, s93
	s_cbranch_scc1 .Lsel_int
	s_branch .Lsel_edge
	s_and_b64 vcc, exec, s[38:39]
	s_cbranch_vccz .LBB0_2557
	s_and_b64 vcc, exec, s[36:37]
	s_cbranch_vccz .LBB0_2521
	s_waitcnt lgkmcnt(7)
	v_mfma_f32_16x16x32_bf16 v[92:95], v[88:91], v[10:13], 0
	v_add_u32_e32 v119, s4, v141
	v_add_u32_e32 v110, 4, v119
	v_cmp_gt_u32_e32 vcc, 2.0, v110
	s_waitcnt lgkmcnt(5)
	v_mfma_f32_16x16x32_bf16 v[104:107], v[84:87], v[14:17], v[92:95]
	v_mov_b32_e32 v108, 0xf149f2ca
	v_mov_b32_e32 v109, 0xf149f2ca
	v_mfma_f32_16x16x32_bf16 v[92:95], v[80:83], v[10:13], 0
	s_waitcnt lgkmcnt(4)
	v_mfma_f32_16x16x32_bf16 v[100:103], v[76:79], v[14:17], v[92:95]
	s_waitcnt lgkmcnt(3)
	v_mfma_f32_16x16x32_bf16 v[92:95], v[72:75], v[10:13], 0
	s_waitcnt lgkmcnt(1)
	v_mfma_f32_16x16x32_bf16 v[96:99], v[68:71], v[14:17], v[92:95]
	v_mfma_f32_16x16x32_bf16 v[92:95], v[60:63], v[10:13], 0
	s_waitcnt lgkmcnt(0)
	v_mfma_f32_16x16x32_bf16 v[92:95], v[64:67], v[14:17], v[92:95]
	s_and_saveexec_b64 s[12:13], vcc
	s_cbranch_execz .LBB0_2488
	v_min_u32_e32 v109, 0x80, v110
	v_lshl_add_u32 v109, v109, 6, v177
	ds_read_b32 v109, v109
	s_waitcnt lgkmcnt(0)
	v_add_f32_e32 v109, v104, v109

; template <int CGM>
; __device__ __forceinline__ void step_int(const bf16x8 (&kf)[4][2], const bf16x8 (&q)[2][2], float farb, const bool (&selq)[2],
;                                          float (&m)[2], float (&l)[2], f32x4 (&o)[2][4], const unsigned char* Vs, int r, int fq) {
;     f32x4 s[2][4]; float mx[2] = {-1e30f, -1e30f};
; #pragma unroll
;     for (int cg_ = 0; cg_ < 2; ++cg_) if ((CGM >> cg_) & 1) { qk(s[cg_], kf, q[cg_], selq[cg_] ? farb - m[cg_] : -1e30f); mx[cg_] = red_max4(max16v(s[cg_])); }
;     if (__any(mx[0] > 0.f || mx[1] > 0.f)) {
; #pragma unroll
;         for (int cg_ = 0; cg_ < 2; ++cg_) if ((CGM >> cg_) & 1) {
;             const float d = fmaxf(mx[cg_], 0.f), sc = __builtin_amdgcn_exp2f(-d); m[cg_] += d; l[cg_] *= sc;
; #pragma unroll
;             for (int df = 0; df < 4; ++df) o[cg_][df] *= sc;
; #pragma unroll
;             for (int f = 0; f < 4; ++f) s[cg_][f] -= d;
;         }
;     }
; template <bool SEL> ...
;     ...
;                 const unsigned char* Ks = lds + OFF_RING + slot * SLOTB; const unsigned char* Vs = Ks + 8192;
;                 bf16x8 kf[4][2]; load_kfrags(kf, Ks, r, fq);
;                 const bool edge = (j >= T - 2) || (wl == 512 && j == T - 8);
.LBB0_2659:
	ds_read_b128 v[80:83], v149
	ds_read_b128 v[72:75], v149 offset:512
	ds_read_b128 v[76:79], v182
	ds_read_b128 v[68:71], v182 offset:512
	ds_read_b128 v[60:63], v149 offset:4096
	ds_read_b128 v[56:59], v149 offset:4608
	ds_read_b128 v[64:67], v182 offset:4096
	ds_read_b128 v[52:55], v182 offset:4608
	s_cmp_ge_i32 s38, s93
	s_cselect_b64 s[6:7], -1, 0
	s_cmp_eq_u32 s29, s4
	s_cselect_b64 s[8:9], -1, 0
	s_or_b64 s[6:7], s[6:7], s[8:9]
	s_andn2_b64 vcc, exec, s[6:7]
	s_mov_b64 s[8:9], -1
	s_cbranch_vccz .LBB0_2664
	s_branch .Lwin_int
	v_sub_f32_e32 v84, v18, v156
	v_mov_b32_e32 v85, v84
	v_mov_b32_e32 v86, v84
	v_mov_b32_e32 v87, v84
	s_waitcnt lgkmcnt(7)
	s_nop 0
	v_mfma_f32_16x16x32_bf16 v[88:91], v[80:83], v[2:5], v[84:87]
	s_waitcnt lgkmcnt(5)
	v_mfma_f32_16x16x32_bf16 v[96:99], v[76:79], v[6:9], v[88:91]
	v_mfma_f32_16x16x32_bf16 v[88:91], v[72:75], v[2:5], v[84:87]
	s_waitcnt lgkmcnt(4)
	v_mfma_f32_16x16x32_bf16 v[92:95], v[68:71], v[6:9], v[88:91]
	s_waitcnt lgkmcnt(3)
	v_mfma_f32_16x16x32_bf16 v[88:91], v[60:63], v[2:5], v[84:87]
	s_waitcnt lgkmcnt(2)
	v_mfma_f32_16x16x32_bf16 v[84:87], v[56:59], v[2:5], v[84:87]
	s_waitcnt lgkmcnt(1)
	v_mfma_f32_16x16x32_bf16 v[88:91], v[64:67], v[6:9], v[88:91]
	s_waitcnt lgkmcnt(0)
	v_mfma_f32_16x16x32_bf16 v[84:87], v[52:55], v[6:9], v[84:87]
	v_sub_f32_e32 v102, v18, v157
	v_mov_b32_e32 v103, v102
	v_mov_b32_e32 v104, v102
	v_mov_b32_e32 v105, v102
	v_max3_f32 v112, v96, v97, v98
	v_max3_f32 v113, v99, v92, v93
	v_mfma_f32_16x16x32_bf16 v[106:109], v[80:83], v[10:13], v[102:105]
	v_max3_f32 v114, v94, v95, v88
	v_max3_f32 v115, v89, v90, v91
	v_mfma_f32_16x16x32_bf16 v[128:131], v[76:79], v[14:17], v[106:109]
	v_max3_f32 v112, v112, v84, v85
	v_max3_f32 v113, v113, v86, v87
	v_mfma_f32_16x16x32_bf16 v[106:109], v[72:75], v[10:13], v[102:105]
	v_max3_f32 v112, v112, v113, v114
	v_max3_f32 v100, v112, v115, v115
	v_mfma_f32_16x16x32_bf16 v[136:139], v[68:71], v[14:17], v[106:109]
	v_mov_b32_e32 v101, v100
	v_mfma_f32_16x16x32_bf16 v[106:109], v[60:63], v[10:13], v[102:105]
	v_mfma_f32_16x16x32_bf16 v[102:105], v[56:59], v[10:13], v[102:105]
	v_permlane16_swap_b32_e32 v100, v101
	v_mfma_f32_16x16x32_bf16 v[112:115], v[64:67], v[14:17], v[106:109]
	v_max_f32_e32 v101, v101, v101
	v_max_f32_e32 v100, v100, v100
	v_max_f32_e32 v100, v100, v101
	v_mfma_f32_16x16x32_bf16 v[104:107], v[52:55], v[14:17], v[102:105]
	v_mov_b32_e32 v101, v100
	s_nop 1
	v_permlane32_swap_b32_e32 v100, v101
	v_max_f32_e32 v101, v101, v101
	v_max_f32_e32 v100, v100, v100
	v_max_f32_e32 v100, v100, v101
	v_max3_f32 v101, v128, v129, v130
	v_max3_f32 v108, v113, v114, v115
	v_max3_f32 v102, v131, v136, v137
	v_max3_f32 v101, v101, v104, v105
	v_max3_f32 v103, v138, v139, v112
	v_max3_f32 v102, v102, v106, v107
	v_max3_f32 v101, v101, v102, v103
	v_max3_f32 v101, v101, v108, v108
	v_mov_b32_e32 v102, v101
	s_nop 1
	v_permlane16_swap_b32_e32 v101, v102
	v_max_f32_e32 v102, v102, v102
	v_max_f32_e32 v101, v101, v101
	v_max_f32_e32 v101, v101, v102
	v_mov_b32_e32 v102, v101
	s_nop 1
	v_permlane32_swap_b32_e32 v101, v102
	v_max_f32_e32 v102, v102, v102
	v_max_f32_e32 v101, v101, v101
	v_max_f32_e32 v120, v101, v102
	v_max_f32_e32 v101, v100, v120
	v_cmp_lt_f32_e32 vcc, 0, v101
	s_cbranch_vccz .LBB0_2662
	v_max_f32_e32 v100, v100, v100
	v_max_f32_e32 v184, 0, v100
	v_max_f32_e32 v120, v120, v120
	v_exp_f32_e64 v122, -v184
	v_max_f32_e32 v185, 0, v120
	v_exp_f32_e64 v120, -v185
	v_sub_f32_e32 v96, v96, v184
	v_mov_b32_e32 v121, v122
	v_pk_mul_f32 v[126:127], v[50:51], v[122:123] op_sel_hi:[1,0]
	v_pk_mul_f32 v[124:125], v[48:49], v[122:123] op_sel_hi:[1,0]
	v_pk_mul_f32 v[118:119], v[42:43], v[122:123] op_sel_hi:[1,0]
	v_pk_mul_f32 v[116:117], v[40:41], v[122:123] op_sel_hi:[1,0]
	v_pk_mul_f32 v[102:103], v[34:35], v[122:123] op_sel_hi:[1,0]
	v_pk_mul_f32 v[100:101], v[32:33], v[122:123] op_sel_hi:[1,0]
	v_pk_mul_f32 v[110:111], v[26:27], v[122:123] op_sel_hi:[1,0]
	v_pk_mul_f32 v[108:109], v[24:25], v[122:123] op_sel_hi:[1,0]
	v_sub_f32_e32 v97, v97, v184
	v_sub_f32_e32 v98, v98, v184
	v_sub_f32_e32 v99, v99, v184
	v_sub_f32_e32 v92, v92, v184
	v_sub_f32_e32 v93, v93, v184
	v_sub_f32_e32 v94, v94, v184
	v_sub_f32_e32 v95, v95, v184
	v_sub_f32_e32 v88, v88, v184
	v_sub_f32_e32 v89, v89, v184
	v_sub_f32_e32 v90, v90, v184
	v_sub_f32_e32 v91, v91, v184
	v_sub_f32_e32 v84, v84, v184
	v_sub_f32_e32 v85, v85, v184
	v_sub_f32_e32 v86, v86, v184
	v_sub_f32_e32 v87, v87, v184
	v_pk_add_f32 v[158:159], v[156:157], v[184:185]
	v_pk_mul_f32 v[160:161], v[154:155], v[120:121]
	v_pk_mul_f32 v[146:147], v[46:47], v[120:121] op_sel_hi:[1,0]
	v_pk_mul_f32 v[144:145], v[44:45], v[120:121] op_sel_hi:[1,0]
	v_pk_mul_f32 v[142:143], v[38:39], v[120:121] op_sel_hi:[1,0]
	v_pk_mul_f32 v[140:141], v[36:37], v[120:121] op_sel_hi:[1,0]
	v_pk_mul_f32 v[134:135], v[30:31], v[120:121] op_sel_hi:[1,0]
	v_pk_mul_f32 v[132:133], v[28:29], v[120:121] op_sel_hi:[1,0]
	v_pk_mul_f32 v[122:123], v[22:23], v[120:121] op_sel_hi:[1,0]
	v_pk_mul_f32 v[120:121], v[20:21], v[120:121] op_sel_hi:[1,0]
	v_sub_f32_e32 v128, v128, v185
	v_sub_f32_e32 v129, v129, v185
	v_sub_f32_e32 v130, v130, v185
	v_sub_f32_e32 v131, v131, v185
	v_sub_f32_e32 v136, v136, v185
	v_sub_f32_e32 v137, v137, v185
	v_sub_f32_e32 v138, v138, v185
	v_sub_f32_e32 v139, v139, v185
	v_sub_f32_e32 v112, v112, v185
	v_sub_f32_e32 v113, v113, v185
	v_sub_f32_e32 v114, v114, v185
	v_sub_f32_e32 v115, v115, v185
	v_sub_f32_e32 v104, v104, v185
	v_sub_f32_e32 v105, v105, v185
	v_sub_f32_e32 v106, v106, v185
	v_sub_f32_e32 v107, v107, v185
	s_branch .LBB0_2663
